# DQK=64 fast path: e0 row-sum adds/cvt/permlanes moved from the step head into the QK MFMA gaps (MFMA-first head)
# speedup vs baseline: 1.0121x; 1.0063x over previous
; __device__ __forceinline__ void finishSM(f32x16& p0, f32x16& p1, float alpha, float& l_reg, bf16x8& pa0, bf16x8& pa1, bf16x8& pa2, bf16x8& pa3) {
; #pragma unroll
;   for (int r = 0; r < 16; ++r) p1[r] = __builtin_amdgcn_exp2f(p1[r]);
;   float ps = 0;
; #pragma unroll
;   for (int r = 0; r < 16; ++r) ps += p0[r];
; #pragma unroll
;   for (int r = 0; r < 16; ++r) ps += p1[r];
;   { auto rr = __builtin_amdgcn_permlane32_swap(__float_as_uint(ps), __float_as_uint(ps), false, false);
;     ps = __uint_as_float(rr[0]) + __uint_as_float(rr[1]); }
;   l_reg = l_reg * alpha + ps;
;     ...
;   PK4(p0, 0, pa0); PK4(p0, 8, pa1); PK4(p1, 0, pa2); PK4(p1, 8, pa3);
;     ...
; }
; template <int DQK> __device__ __forceinline__ void qkt(f32x16& p0, f32x16& p1, const char* Ks, const bf16x8* qr, int r32, int hi, const f32x16& negm) {
; #pragma unroll
;   for (int d0 = 0; d0 < DQK / 16; ++d0) { const int cb = (d0 * 16 + hi * 8) * 2;
;     const bf16x8 b0 = *reinterpret_cast<const bf16x8*>(Ks + (DQK == 128 ? KSWZ(r32, cb) : KSWZ64(r32, cb)));
;     const bf16x8 b1 = *reinterpret_cast<const bf16x8*>(Ks + (DQK == 128 ? KSWZ(32 + r32, cb) : KSWZ64(32 + r32, cb)));
;     if (d0 == 0) { p0 = __builtin_amdgcn_mfma_f32_32x32x16_bf16(b0, qr[0], negm, 0, 0, 0); p1 = __builtin_amdgcn_mfma_f32_32x32x16_bf16(b1, qr[0], negm, 0, 0, 0); }
;     else { p0 = __builtin_amdgcn_mfma_f32_32x32x16_bf16(b0, qr[d0], p0, 0, 0, 0); p1 = __builtin_amdgcn_mfma_f32_32x32x16_bf16(b1, qr[d0], p1, 0, 0, 0); } }
; }
; __device__ __forceinline__ int v_st(int k, int c) { const int kk = (k & ~0xC) | ((k & 4) << 1) | ((k & 8) >> 1); return ((kk >> 3) * 4 + (c >> 5)) * 512 + ((kk & 7) * 32 + (c & 31)) * 2; }
; __device__ __forceinline__ int v_rd_base(int lane) { return ((lane & 3) << 3) | (((lane >> 2) & 3) << 6) | (((lane >> 4) & 1) << 5) | (((lane >> 5) & 1) << 8); }
; template <int OFF> __device__ __forceinline__ s16x4 tr_read(int vb) {
;   s16x4 r; asm volatile("ds_read_b64_tr_b16 %0, %1 offset:%2" : "=&v"(r) : "v"(vb), "i"(OFF) : "memory"); return r;
; }
; template <int D0> __device__ __forceinline__ void pv_one(f32x16& od, int vb, bf16x8 pa0, bf16x8 pa1, bf16x8 pa2, bf16x8 pa3) {
;   const s16x4 l0 = tr_read<v_rd_off(D0, 0, 0)>(vb), h0 = tr_read<v_rd_off(D0, 0, 1)>(vb), l1 = tr_read<v_rd_off(D0, 1, 0)>(vb), h1 = tr_read<v_rd_off(D0, 1, 1)>(vb);
.LBB0_218:
	s_add_i32 s99, s19, 0xffffff61
	s_cmp_lt_u32 s99, 0xfffffea3
	s_cbranch_scc0 .Lold_h1
	s_cmp_le_u32 s18, s47
	s_cbranch_scc0 .Lold_h1
	ds_read_b128 v[180:183], v225 offset:53248
	ds_read_b128 v[116:119], v225 offset:49152
	ds_read_b128 v[184:187], v227 offset:53248
	ds_read_b128 v[68:71], v227 offset:49152
	ds_read_b128 v[72:75], v228 offset:53248
	ds_read_b128 v[206:209], v228 offset:49152
	s_waitcnt lgkmcnt(6)
	v_cmp_neq_f32_e32 vcc, v133, v66
	s_cbranch_vccnz .Lcupd_f1
.Lcret_f1:
	v_add_f32_e32 v0, 0, v148
	v_add_f32_e32 v0, v178, v0
	v_add_f32_e32 v0, v146, v0
	v_add_f32_e32 v0, v149, v0
	s_waitcnt lgkmcnt(4)
	v_mfma_f32_32x32x16_bf16 v[84:99], v[116:119], v[162:165], v[236:251]
	v_mfma_f32_32x32x16_bf16 v[116:131], v[180:183], v[162:165], v[236:251]
	ds_read_b128 v[180:183], v226 offset:53248
	v_add_f32_e32 v0, v144, v0
	v_add_f32_e32 v0, v147, v0
	v_add_f32_e32 v0, v143, v0
	v_add_f32_e32 v0, v145, v0
	v_add_f32_e32 v0, v137, v0
	v_add_f32_e32 v0, v139, v0
	s_waitcnt lgkmcnt(3)
	v_mfma_f32_32x32x16_bf16 v[116:131], v[184:187], v[158:161], v[116:131]
	v_add_f32_e32 v0, v136, v0
	v_add_f32_e32 v0, v138, v0
	v_add_f32_e32 v0, v135, v0
	v_add_f32_e32 v0, v142, v0
	v_add_f32_e32 v0, v140, v0
	v_add_f32_e32 v0, v141, v0
	v_mfma_f32_32x32x16_bf16 v[84:99], v[68:71], v[158:161], v[84:99]
	ds_read_b128 v[184:187], v226 offset:49152
	v_cvt_pk_bf16_f32 v76, v148, v178
	v_cvt_pk_bf16_f32 v77, v146, v149
	v_cvt_pk_bf16_f32 v78, v144, v147
	v_cvt_pk_bf16_f32 v79, v143, v145
	v_lshl_add_u64 v[148:149], v[194:195], 0, s[0:1]
	v_lshl_add_u64 v[196:197], v[192:193], 0, s[0:1]
	s_waitcnt lgkmcnt(2)
	v_mfma_f32_32x32x16_bf16 v[116:131], v[72:75], v[154:157], v[116:131]
	v_cvt_pk_bf16_f32 v80, v137, v139
	v_cvt_pk_bf16_f32 v81, v136, v138
	v_cvt_pk_bf16_f32 v82, v135, v142
	v_cvt_pk_bf16_f32 v83, v140, v141
	s_mov_b32 s4, 0x102b1000
	v_add_co_u32_e64 v132, s[4:5], s4, v148
	v_mfma_f32_32x32x16_bf16 v[84:99], v[206:209], v[154:157], v[84:99]
	ds_read_b64_tr_b16 v[134:135], v223 offset:0
	ds_read_b64_tr_b16 v[136:137], v223 offset:0x800
	ds_read_b64_tr_b16 v[138:139], v223 offset:0x200
	ds_read_b64_tr_b16 v[140:141], v223 offset:0xa00
	ds_read_b64_tr_b16 v[142:143], v223 offset:0x400
	ds_read_b64_tr_b16 v[144:145], v223 offset:0xc00
	ds_read_b64_tr_b16 v[198:199], v223 offset:0x600
	ds_read_b64_tr_b16 v[200:201], v223 offset:0xe00
	v_permlane32_swap_b32_e32 v76, v78
	v_permlane32_swap_b32_e32 v77, v79
	v_addc_co_u32_e64 v133, s[4:5], 0, v149, s[4:5]
	s_mov_b32 s4, 0x102f9000
	v_add_co_u32_e64 v202, s[4:5], s4, v148
	s_waitcnt lgkmcnt(8)
	v_mfma_f32_32x32x16_bf16 v[116:131], v[180:183], v[150:153], v[116:131]
	v_addc_co_u32_e64 v203, s[4:5], 0, v149, s[4:5]
	s_mov_b32 s4, 0x102b0000
	v_add_co_u32_e64 v204, s[4:5], s4, v196
	v_permlane32_swap_b32_e32 v80, v82
	v_permlane32_swap_b32_e32 v81, v83
	v_mfma_f32_32x32x16_bf16 v[84:99], v[184:187], v[150:153], v[84:99]
	v_addc_co_u32_e64 v205, s[4:5], 0, v197, s[4:5]
	global_load_dwordx4 v[178:181], v[132:133], off
	global_load_dwordx4 v[182:185], v[202:203], off
	global_load_dwordx4 v[186:189], v[204:205], off offset:2048
	s_waitcnt lgkmcnt(6)
	v_mfma_f32_32x32x16_bf16 v[50:65], v[76:79], v[134:137], v[50:65]
	ds_read_b64_tr_b16 v[134:135], v223 offset:0x1000
	ds_read_b64_tr_b16 v[136:137], v223 offset:0x1800
	v_exp_f32_e32 v68, v100
	v_exp_f32_e32 v69, v101
	v_add_f32_e32 v0, v68, v0
	s_waitcnt lgkmcnt(6)
	v_mfma_f32_32x32x16_bf16 v[34:49], v[76:79], v[138:141], v[34:49]
	ds_read_b64_tr_b16 v[138:139], v223 offset:0x1200
	ds_read_b64_tr_b16 v[140:141], v223 offset:0x1a00
	v_exp_f32_e32 v70, v102
	v_add_f32_e32 v0, v69, v0
	v_exp_f32_e32 v71, v103
	v_add_f32_e32 v0, v70, v0
	s_waitcnt lgkmcnt(6)
	v_mfma_f32_32x32x16_bf16 v[18:33], v[76:79], v[142:145], v[18:33]
	ds_read_b64_tr_b16 v[142:143], v223 offset:0x1400
	ds_read_b64_tr_b16 v[144:145], v223 offset:0x1c00
	v_exp_f32_e32 v72, v104
	v_add_f32_e32 v0, v71, v0
	v_exp_f32_e32 v73, v105
	v_add_f32_e32 v0, v72, v0
	s_waitcnt lgkmcnt(6)
; #define SBAR() __builtin_amdgcn_sched_barrier(0)
; template <bool FIRST> __device__ __forceinline__ void partialSM(f32x16& p0, f32x16& p1, float& m_reg, float& alpha, f32x16& negm, float c_cur) {
;   float pmax = p0[0];
; #pragma unroll
;   for (int r = 1; r < 16; ++r) pmax = fmaxf(pmax, p0[r]);
; #pragma unroll
;   for (int r = 0; r < 16; ++r) pmax = fmaxf(pmax, p1[r]);
;   { auto rr = __builtin_amdgcn_permlane32_swap(__float_as_uint(pmax), __float_as_uint(pmax), false, false);
;     pmax = fmaxf(__uint_as_float(rr[0]), __uint_as_float(rr[1])); }
; template <int OFF> __device__ __forceinline__ s16x4 tr_read(int vb) {
;   s16x4 r; asm volatile("ds_read_b64_tr_b16 %0, %1 offset:%2" : "=&v"(r) : "v"(vb), "i"(OFF) : "memory"); return r;
; }
; template <int D0> __device__ __forceinline__ void pv_one(f32x16& od, int vb, bf16x8 pa0, bf16x8 pa1, bf16x8 pa2, bf16x8 pa3) {
;   const s16x4 l0 = tr_read<v_rd_off(D0, 0, 0)>(vb), h0 = tr_read<v_rd_off(D0, 0, 1)>(vb), l1 = tr_read<v_rd_off(D0, 1, 0)>(vb), h1 = tr_read<v_rd_off(D0, 1, 1)>(vb);
;   const s16x4 l2 = tr_read<v_rd_off(D0, 2, 0)>(vb), h2 = tr_read<v_rd_off(D0, 2, 1)>(vb), l3 = tr_read<v_rd_off(D0, 3, 0)>(vb), h3 = tr_read<v_rd_off(D0, 3, 1)>(vb);
;   asm volatile("s_waitcnt lgkmcnt(0)" ::: "memory"); SBAR();
;     ...
;   od = __builtin_amdgcn_mfma_f32_32x32x16_bf16(pa0, PK(l0, h0), od, 0, 0, 0);
;   od = __builtin_amdgcn_mfma_f32_32x32x16_bf16(pa1, PK(l1, h1), od, 0, 0, 0);
;   od = __builtin_amdgcn_mfma_f32_32x32x16_bf16(pa2, PK(l2, h2), od, 0, 0, 0);
;   od = __builtin_amdgcn_mfma_f32_32x32x16_bf16(pa3, PK(l3, h3), od, 0, 0, 0);
;     ...
; }
; __device__ __forceinline__ void pv_d0(f32x16* o, int vb, bf16x8 pa0, bf16x8 pa1, bf16x8 pa2, bf16x8 pa3) {
;   pv_one<0>(o[0], vb, pa0, pa1, pa2, pa3); pv_one<1>(o[1], vb, pa0, pa1, pa2, pa3); pv_one<2>(o[2], vb, pa0, pa1, pa2, pa3); pv_one<3>(o[3], vb, pa0, pa1, pa2, pa3);
; }
	v_mfma_f32_32x32x16_bf16 v[2:17], v[76:79], v[198:201], v[2:17]
	ds_read_b64_tr_b16 v[198:199], v223 offset:0x1600
	ds_read_b64_tr_b16 v[200:201], v223 offset:0x1e00
	v_exp_f32_e32 v74, v106
	v_add_f32_e32 v0, v73, v0
	v_exp_f32_e32 v75, v107
	v_add_f32_e32 v0, v74, v0
	v_add_f32_e32 v0, v75, v0
	s_waitcnt lgkmcnt(6)
	v_mfma_f32_32x32x16_bf16 v[50:65], v[80:83], v[134:137], v[50:65]
	ds_read_b64_tr_b16 v[134:135], v223 offset:0x2000
	ds_read_b64_tr_b16 v[136:137], v223 offset:0x2800
	v_cvt_pk_bf16_f32 v100, v68, v69
	v_cvt_pk_bf16_f32 v101, v70, v71
	v_cvt_pk_bf16_f32 v102, v72, v73
	v_cvt_pk_bf16_f32 v103, v74, v75
	s_waitcnt lgkmcnt(6)
	v_mfma_f32_32x32x16_bf16 v[34:49], v[80:83], v[138:141], v[34:49]
	ds_read_b64_tr_b16 v[138:139], v223 offset:0x2200
	ds_read_b64_tr_b16 v[140:141], v223 offset:0x2a00
	v_exp_f32_e32 v68, v108
	v_exp_f32_e32 v69, v109
	v_permlane32_swap_b32_e32 v100, v102
	v_permlane32_swap_b32_e32 v101, v103
	s_waitcnt lgkmcnt(6)
	v_mfma_f32_32x32x16_bf16 v[18:33], v[80:83], v[142:145], v[18:33]
	ds_read_b64_tr_b16 v[142:143], v223 offset:0x2400
	ds_read_b64_tr_b16 v[144:145], v223 offset:0x2c00
	v_exp_f32_e32 v70, v110
	v_exp_f32_e32 v71, v111
	v_exp_f32_e32 v72, v112
	s_waitcnt lgkmcnt(6)
	v_mfma_f32_32x32x16_bf16 v[2:17], v[80:83], v[198:201], v[2:17]
	ds_read_b64_tr_b16 v[198:199], v223 offset:0x2600
	ds_read_b64_tr_b16 v[200:201], v223 offset:0x2e00
	v_exp_f32_e32 v73, v113
	v_exp_f32_e32 v74, v114
	v_exp_f32_e32 v75, v115
	s_waitcnt lgkmcnt(6)
	v_mfma_f32_32x32x16_bf16 v[50:65], v[100:103], v[134:137], v[50:65]
	ds_read_b64_tr_b16 v[134:135], v223 offset:0x3000
	ds_read_b64_tr_b16 v[136:137], v223 offset:0x3800
	v_add_f32_e32 v0, v68, v0
	v_add_f32_e32 v0, v69, v0
	v_add_f32_e32 v0, v70, v0
	v_add_f32_e32 v0, v71, v0
	s_waitcnt lgkmcnt(6)
	v_mfma_f32_32x32x16_bf16 v[34:49], v[100:103], v[138:141], v[34:49]
	ds_read_b64_tr_b16 v[138:139], v223 offset:0x3200
	ds_read_b64_tr_b16 v[140:141], v223 offset:0x3a00
	v_add_f32_e32 v0, v72, v0
	v_add_f32_e32 v0, v73, v0
	v_add_f32_e32 v0, v74, v0
	v_add_f32_e32 v0, v75, v0
	v_mov_b32_e32 v231, v0
	s_waitcnt lgkmcnt(6)
	v_mfma_f32_32x32x16_bf16 v[18:33], v[100:103], v[142:145], v[18:33]
	ds_read_b64_tr_b16 v[142:143], v223 offset:0x3400
	ds_read_b64_tr_b16 v[144:145], v223 offset:0x3c00
	v_cvt_pk_bf16_f32 v104, v68, v69
	v_cvt_pk_bf16_f32 v105, v70, v71
	v_cvt_pk_bf16_f32 v106, v72, v73
	v_cvt_pk_bf16_f32 v107, v74, v75
	v_permlane32_swap_b32_e32 v0, v231
	s_waitcnt lgkmcnt(6)
	v_mfma_f32_32x32x16_bf16 v[2:17], v[100:103], v[198:201], v[2:17]
	ds_read_b64_tr_b16 v[198:199], v223 offset:0x3600
	ds_read_b64_tr_b16 v[200:201], v223 offset:0x3e00
	v_permlane32_swap_b32_e32 v104, v106
	v_permlane32_swap_b32_e32 v105, v107
	v_max_f32_e32 v132, v84, v85
	v_max3_f32 v132, v132, v86, v87
	v_max3_f32 v132, v132, v88, v89
	s_waitcnt lgkmcnt(6)
	v_mfma_f32_32x32x16_bf16 v[50:65], v[104:107], v[134:137], v[50:65]
	v_max3_f32 v132, v132, v90, v91
	v_max3_f32 v132, v132, v92, v93
	v_max3_f32 v132, v132, v94, v95
	v_max3_f32 v132, v132, v96, v97
	v_max3_f32 v132, v132, v98, v99
	s_waitcnt lgkmcnt(4)
	v_mfma_f32_32x32x16_bf16 v[34:49], v[104:107], v[138:141], v[34:49]
	v_max3_f32 v132, v132, v116, v117
	v_max3_f32 v132, v132, v118, v119
	v_max3_f32 v132, v132, v120, v121
	v_max3_f32 v132, v132, v122, v123
	v_max3_f32 v132, v132, v124, v125
	s_waitcnt lgkmcnt(2)
	v_mfma_f32_32x32x16_bf16 v[18:33], v[104:107], v[142:145], v[18:33]
	v_max3_f32 v132, v132, v126, v127
	v_max3_f32 v132, v132, v128, v129
	v_max3_f32 v132, v132, v130, v131
	v_mov_b32_e32 v133, v132
	s_waitcnt lgkmcnt(0)
	v_mfma_f32_32x32x16_bf16 v[2:17], v[104:107], v[198:201], v[2:17]
	v_permlane32_swap_b32_e32 v132, v133
	v_max_f32_e32 v100, v132, v133
	s_branch .Ljoin_h1

; __device__ __forceinline__ void finishSM(f32x16& p0, f32x16& p1, float alpha, float& l_reg, bf16x8& pa0, bf16x8& pa1, bf16x8& pa2, bf16x8& pa3) {
; #pragma unroll
;   for (int r = 0; r < 16; ++r) p1[r] = __builtin_amdgcn_exp2f(p1[r]);
;   float ps = 0;
; #pragma unroll
;   for (int r = 0; r < 16; ++r) ps += p0[r];
; #pragma unroll
;   for (int r = 0; r < 16; ++r) ps += p1[r];
;   { auto rr = __builtin_amdgcn_permlane32_swap(__float_as_uint(ps), __float_as_uint(ps), false, false);
;     ps = __uint_as_float(rr[0]) + __uint_as_float(rr[1]); }
;   l_reg = l_reg * alpha + ps;
;     ...
;   PK4(p0, 0, pa0); PK4(p0, 8, pa1); PK4(p1, 0, pa2); PK4(p1, 8, pa3);
;     ...
; }
; template <int DQK> __device__ __forceinline__ void qkt(f32x16& p0, f32x16& p1, const char* Ks, const bf16x8* qr, int r32, int hi, const f32x16& negm) {
; #pragma unroll
;   for (int d0 = 0; d0 < DQK / 16; ++d0) { const int cb = (d0 * 16 + hi * 8) * 2;
;     const bf16x8 b0 = *reinterpret_cast<const bf16x8*>(Ks + (DQK == 128 ? KSWZ(r32, cb) : KSWZ64(r32, cb)));
;     const bf16x8 b1 = *reinterpret_cast<const bf16x8*>(Ks + (DQK == 128 ? KSWZ(32 + r32, cb) : KSWZ64(32 + r32, cb)));
;     if (d0 == 0) { p0 = __builtin_amdgcn_mfma_f32_32x32x16_bf16(b0, qr[0], negm, 0, 0, 0); p1 = __builtin_amdgcn_mfma_f32_32x32x16_bf16(b1, qr[0], negm, 0, 0, 0); }
;     else { p0 = __builtin_amdgcn_mfma_f32_32x32x16_bf16(b0, qr[d0], p0, 0, 0, 0); p1 = __builtin_amdgcn_mfma_f32_32x32x16_bf16(b1, qr[d0], p1, 0, 0, 0); } }
; }
; __device__ __forceinline__ int v_st(int k, int c) { const int kk = (k & ~0xC) | ((k & 4) << 1) | ((k & 8) >> 1); return ((kk >> 3) * 4 + (c >> 5)) * 512 + ((kk & 7) * 32 + (c & 31)) * 2; }
; __device__ __forceinline__ int v_rd_base(int lane) { return ((lane & 3) << 3) | (((lane >> 2) & 3) << 6) | (((lane >> 4) & 1) << 5) | (((lane >> 5) & 1) << 8); }
; template <int OFF> __device__ __forceinline__ s16x4 tr_read(int vb) {
;   s16x4 r; asm volatile("ds_read_b64_tr_b16 %0, %1 offset:%2" : "=&v"(r) : "v"(vb), "i"(OFF) : "memory"); return r;
; }
; template <int D0> __device__ __forceinline__ void pv_one(f32x16& od, int vb, bf16x8 pa0, bf16x8 pa1, bf16x8 pa2, bf16x8 pa3) {
;   const s16x4 l0 = tr_read<v_rd_off(D0, 0, 0)>(vb), h0 = tr_read<v_rd_off(D0, 0, 1)>(vb), l1 = tr_read<v_rd_off(D0, 1, 0)>(vb), h1 = tr_read<v_rd_off(D0, 1, 1)>(vb);
.LBB0_235:
	s_add_i32 s4, s25, -1
	s_add_i32 s99, s19, 0xffffffa1
	s_cmp_lt_u32 s99, 0xfffffea3
	s_cbranch_scc0 .Lold_h2
	s_add_i32 s99, s18, 64
	s_cmp_le_u32 s99, s47
	s_cbranch_scc0 .Lold_h2
	ds_read_b128 v[84:87], v225 offset:36864
	ds_read_b128 v[100:103], v225 offset:32768
	ds_read_b128 v[88:91], v227 offset:36864
	ds_read_b128 v[134:137], v227 offset:32768
	ds_read_b128 v[138:141], v228 offset:36864
	ds_read_b128 v[142:145], v228 offset:32768
	s_waitcnt lgkmcnt(6)
	v_cmp_neq_f32_e32 vcc, v133, v66
	s_cbranch_vccnz .Lcupd_f2
.Lcret_f2:
	v_add_f32_e32 v235, 0, v219
	v_add_f32_e32 v235, v233, v235
	v_add_f32_e32 v235, v209, v235
	v_add_f32_e32 v235, v220, v235
	s_waitcnt lgkmcnt(4)
	v_mfma_f32_32x32x16_bf16 v[68:83], v[100:103], v[162:165], v[236:251]
	v_mfma_f32_32x32x16_bf16 v[100:115], v[84:87], v[162:165], v[236:251]
	ds_read_b128 v[84:87], v226 offset:36864
	v_add_f32_e32 v235, v207, v235
	v_add_f32_e32 v235, v218, v235
	v_add_f32_e32 v235, v206, v235
	v_add_f32_e32 v235, v208, v235
	v_add_f32_e32 v235, v203, v235
	v_add_f32_e32 v235, v205, v235
	s_waitcnt lgkmcnt(3)
	v_mfma_f32_32x32x16_bf16 v[100:115], v[88:91], v[158:161], v[100:115]
	v_add_f32_e32 v235, v201, v235
	v_add_f32_e32 v235, v204, v235
	v_add_f32_e32 v235, v199, v235
	v_add_f32_e32 v235, v202, v235
	v_add_f32_e32 v235, v198, v235
	v_add_f32_e32 v235, v200, v235
	v_mfma_f32_32x32x16_bf16 v[68:83], v[134:137], v[158:161], v[68:83]
	ds_read_b128 v[88:91], v226 offset:32768
	v_cvt_pk_bf16_f32 v92, v219, v233
	v_cvt_pk_bf16_f32 v93, v209, v220
	v_cvt_pk_bf16_f32 v94, v207, v218
	v_cvt_pk_bf16_f32 v95, v206, v208
	v_add_co_u32_e32 v132, vcc, 0x10341000, v148
	s_waitcnt lgkmcnt(2)
	v_mfma_f32_32x32x16_bf16 v[100:115], v[138:141], v[154:157], v[100:115]
	v_cvt_pk_bf16_f32 v96, v203, v205
	v_cvt_pk_bf16_f32 v97, v201, v204
	v_addc_co_u32_e32 v133, vcc, 0, v149, vcc
	v_add_co_u32_e32 v174, vcc, 0x10389000, v148
	v_cvt_pk_bf16_f32 v98, v199, v202
	v_cvt_pk_bf16_f32 v99, v198, v200
	v_addc_co_u32_e32 v175, vcc, 0, v149, vcc
	v_mfma_f32_32x32x16_bf16 v[68:83], v[142:145], v[154:157], v[68:83]
	ds_read_b64_tr_b16 v[134:135], v211 offset:0
	ds_read_b64_tr_b16 v[136:137], v211 offset:0x800
	ds_read_b64_tr_b16 v[138:139], v211 offset:0x200
	ds_read_b64_tr_b16 v[140:141], v211 offset:0xa00
	ds_read_b64_tr_b16 v[142:143], v211 offset:0x400
	ds_read_b64_tr_b16 v[144:145], v211 offset:0xc00
	ds_read_b64_tr_b16 v[146:147], v211 offset:0x600
	ds_read_b64_tr_b16 v[148:149], v211 offset:0xe00
	v_permlane32_swap_b32_e32 v92, v94
	v_permlane32_swap_b32_e32 v93, v95
	v_add_co_u32_e32 v176, vcc, 0x10340000, v196
	s_waitcnt lgkmcnt(8)
	v_mfma_f32_32x32x16_bf16 v[100:115], v[84:87], v[150:153], v[100:115]
	v_permlane32_swap_b32_e32 v96, v98
	v_permlane32_swap_b32_e32 v97, v99
	v_mfma_f32_32x32x16_bf16 v[68:83], v[88:91], v[150:153], v[68:83]
	v_addc_co_u32_e32 v177, vcc, 0, v197, vcc
	s_cmp_ge_u32 s4, s28
	s_cbranch_scc1 .Lnold_h2
	global_load_dwordx4 v[166:169], v[132:133], off
	global_load_dwordx4 v[170:173], v[174:175], off
	global_load_dwordx4 v[174:177], v[176:177], off offset:2048
